# v022 + saddr form for the two first-phase pieces of the residual-epilogue loop + LDS fragment-base folding for the remaining in-proj loop
# speedup vs baseline: 1.0535x; 1.0015x over previous
; #define PG8_STAGE(bufoff, gbase, voff) do { _Pragma("unroll") for (int _i = 0; _i < 2; ++_i) \
;         __builtin_amdgcn_global_load_lds((const unsigned*)((const char*)(gbase) + (voff)[_i]), (LAS unsigned*)(lds + (bufoff) + ldsw + _i * 8192), 16, 0, 0); } while (0)
; #define PG8_WAIT_V(n) asm volatile("s_waitcnt vmcnt(" #n ")" ::: "memory")
; #define PG8_BAR __builtin_amdgcn_s_barrier()
; template <class Epi>
; __device__ __forceinline__ void gemm_phase(LAS unsigned char* lds, const Gemm g, const StaticOrder& S, const Epi& E) {
;     ...
;     for (int i = 0; i < 2; ++i) { int R, C; stage_rc(tid * 16 + i * 8192, R, C); const int Rb = Epi::PERM ? ((R & ~31) + perm32(R & 31)) : R;
;         voffA[i] = (unsigned)(R * K + C) * 2u; voffB[i] = (unsigned)(Rb * K + C) * 2u; }
;     const size_t kstep = (size_t)(BK * 2);
;     const size_t hstep = (size_t)HALF * K * 2;
;     const size_t tstep = 2 * hstep;
;     const unsigned ldsw = (unsigned)wid * 1024u;
;     const int aoff = lds_byte(wr * 64 + fr, fq * 8), boff = lds_byte(wc * 32 + fr, fq * 8);
;     ...
;     PG8_WAIT_V(4); PG8_BAR;
;     PG8_STAGE(PG8_SB(1, 0), cB + kstep, voffB); PG8_STAGE(PG8_SA(1, 0), cA + kstep, voffA); PG8_STAGE(PG8_SB(1, 1), cB + hstep + kstep, voffB);
;     PG8_WAIT_V(6); PG8_BAR;
.LBB0_485:
	v_lshrrev_b32_e32 v16, 1, v14
	v_and_b32_e32 v16, 24, v16
	v_and_b32_e32 v15, 15, v14
	v_lshlrev_b32_e32 v17, 1, v16
	v_lshlrev_b32_e32 v14, 2, v14
	v_lshl_or_b32 v142, s0, 6, v15
	v_lshl_or_b32 v15, v15, 6, v17
	s_lshl_b32 s0, s0, 13
	v_and_b32_e32 v14, 32, v14
	v_bitop3_b32 v17, v15, s0, v14 bitop3:0xde
	s_lshl_b32 s0, s1, 5
	s_and_b32 s3, s0, 0x60
	s_add_i32 m0, s27, 0x18000
	v_lshl_add_u64 v[6:7], v[6:7], 0, s[58:59]
	s_lshl_b32 s0, s3, 7
	s_waitcnt vmcnt(4)
	s_barrier
	global_load_lds_dwordx4 v[6:7], off
	v_lshl_add_u64 v[4:5], v[4:5], 0, s[58:59]
	s_add_i32 m0, s27, 0x1a000
	s_add_i32 s41, s27, 0x8000
	s_add_i32 s42, s27, 0xa000
	v_bitop3_b32 v143, v15, s0, v14 bitop3:0xde
	v_add_u32_e32 v143, 0x10000, v143
	global_load_lds_dwordx4 v[4:5], off
	v_lshl_add_u64 v[2:3], v[2:3], 0, s[58:59]
	s_mov_b32 m0, s41
	s_add_u32 s0, s30, 0x80080
	global_load_lds_dwordx4 v[2:3], off
	v_lshl_add_u64 v[0:1], v[0:1], 0, s[58:59]
	s_mov_b32 m0, s42
	s_addc_u32 s1, s31, 0
	global_load_lds_dwordx4 v[0:1], off
	s_add_i32 m0, s27, 0x1c000
	v_lshl_add_u64 v[0:1], s[0:1], 0, v[184:185]
	global_load_lds_dwordx4 v[0:1], off
	v_lshl_add_u64 v[0:1], s[0:1], 0, v[132:133]
	s_add_i32 m0, s27, 0x1e000
	s_ashr_i32 s44, s36, 31
	global_load_lds_dwordx4 v[0:1], off
	v_lshlrev_b32_e32 v0, 15, v8
	v_and_b32_e32 v0, 0xffff0000, v0
	v_lshl_add_u32 v0, v9, 12, v0
	v_and_b32_e32 v1, 1, v8
	v_lshl_or_b32 v0, v1, 6, v0
	v_lshl_add_u32 v134, v10, 1, v0
	v_lshlrev_b32_e32 v0, 15, v11
	v_and_b32_e32 v0, 0xffff0000, v0
	s_waitcnt vmcnt(6)
	s_and_b64 s[0:1], s[16:17], exec
	v_lshl_add_u32 v0, v12, 12, v0
	v_and_b32_e32 v1, 1, v11
	s_mov_b32 s0, 0xa000
	v_lshl_or_b32 v0, v1, 6, v0
	s_cselect_b32 s45, 0x1000, s0
	s_mov_b32 s46, 0
	s_cselect_b32 s1, s93, s97
	s_cselect_b32 s0, s92, s96
	v_or_b32_e32 v144, s3, v16
	v_mov_b32_e32 v135, v185
	v_lshl_add_u32 v136, v13, 1, v0
	v_mov_b32_e32 v137, v185
	v_add_u32_e32 v145, 0, v17
	s_barrier
	s_branch .LBB0_487

; #define PG8_STAGE(bufoff, gbase, voff) do { _Pragma("unroll") for (int _i = 0; _i < 2; ++_i) \
;         __builtin_amdgcn_global_load_lds((const unsigned*)((const char*)(gbase) + (voff)[_i]), (LAS unsigned*)(lds + (bufoff) + ldsw + _i * 8192), 16, 0, 0); } while (0)
; #define PG8_LDA(dst, b, h) do { _Pragma("unroll") for (int m = 0; m < 4; ++m) _Pragma("unroll") for (int k = 0; k < 2; ++k) dst[m][k] = *(const LAS bf16x8*)(lds + PG8_SA(b, h) + aoff + m * 2048 + k * 1024); } while (0)
; #define PG8_LDB(dst, b, h) do { _Pragma("unroll") for (int n = 0; n < 2; ++n) _Pragma("unroll") for (int k = 0; k < 2; ++k) dst[n][k] = *(const LAS bf16x8*)(lds + PG8_SB(b, h) + boff + n * 2048 + k * 1024); } while (0)
; #define PG8_MMA(ai, bj, At, Bt) do { __builtin_amdgcn_s_setprio(1); _Pragma("unroll") for (int m = 0; m < 4; ++m) _Pragma("unroll") for (int n = 0; n < 2; ++n) _Pragma("unroll") for (int k = 0; k < 2; ++k) \
;         acc[ai][bj][m][n] = __builtin_amdgcn_mfma_f32_16x16x32_bf16(Bt[n][k], At[m][k], acc[ai][bj][m][n], 0, 0, 0); __builtin_amdgcn_s_setprio(0); } while (0)
; #define PG8_WAIT_V(n) asm volatile("s_waitcnt vmcnt(" #n ")" ::: "memory")
; #define PG8_WAIT_L(n) asm volatile("s_waitcnt lgkmcnt(" #n ")" ::: "memory")
; #define PG8_BAR __builtin_amdgcn_s_barrier()
; template <class Epi>
; __device__ __forceinline__ void gemm_phase(LAS unsigned char* lds, const Gemm g, const StaticOrder& S, const Epi& E) {
;     ...
;             const bool last = (t == nt - 2);
;             const char* a1 = cA + (size_t)(t + 1) * kstep;
;             const char* a2 = last ? nA : cA + (size_t)(t + 2) * kstep; const char* b2 = last ? nB : cB + (size_t)(t + 2) * kstep;
;             const char* a3 = a2 + kstep; const char* b3 = b2 + kstep;
;             PG8_LDB(B0, 0, 0); PG8_SCHED; PG8_LDA(At, 0, 0); PG8_STAGE(PG8_SA(1, 1), a1 + hstep, voffA);
;             PG8_WAIT_L(8); PG8_BAR; PG8_WAIT_L(0); PG8_MMA(0, 0, At, B0); PG8_BAR; PG8_SCHED;
;             PG8_LDB(B1, 0, 1); PG8_STAGE(PG8_SB(0, 0), b2, voffB);
;             PG8_BAR; PG8_WAIT_L(0); PG8_MMA(0, 1, At, B1); PG8_BAR;
;             PG8_LDA(At, 0, 1); PG8_STAGE(PG8_SA(0, 0), a2, voffA);
;             PG8_BAR; PG8_WAIT_L(0); PG8_MMA(1, 0, At, B0); PG8_BAR; PG8_SCHED;
;             PG8_STAGE(PG8_SB(0, 1), b2 + hstep, voffB);
;             PG8_WAIT_V(6); PG8_BAR; PG8_MMA(1, 1, At, B1); PG8_BAR;
.LBB0_490:
	s_add_u32 s30, s8, 0xfff80080
	s_addc_u32 s31, s9, -1
	s_add_i32 s52, 0, 0x10000
	ds_read_b128 v[138:141], v143
	ds_read_b128 v[146:149], v143 offset:1024
	ds_read_b128 v[150:153], v143 offset:2048
	ds_read_b128 v[154:157], v143 offset:3072
	s_cmp_eq_u32 s51, 28
	s_cselect_b32 s35, s3, s31
	s_cselect_b32 s34, s21, s30
	s_cselect_b32 s31, s19, s50
	s_cselect_b32 s30, s43, s47
	s_add_i32 m0, s27, 0xc000
	ds_read_b128 v[158:161], v145
	ds_read_b128 v[162:165], v145 offset:1024
	ds_read_b128 v[166:169], v145 offset:2048
	ds_read_b128 v[170:173], v145 offset:3072
	ds_read_b128 v[174:177], v145 offset:4096
	ds_read_b128 v[178:181], v145 offset:5120
	ds_read_b128 v[204:207], v145 offset:6144
	ds_read_b128 v[208:211], v145 offset:7168
	global_load_lds_dwordx4 v134, s[8:9]
	s_add_i32 m0, s27, 0xe000
	s_nop 0
	global_load_lds_dwordx4 v136, s[8:9]
	s_waitcnt lgkmcnt(8)
	s_barrier
	s_waitcnt lgkmcnt(0)
	v_mfma_f32_16x16x32_bf16 v[124:127], v[138:141], v[158:161], v[124:127]
	v_mfma_f32_16x16x32_bf16 v[124:127], v[146:149], v[162:165], v[124:127]
	v_mfma_f32_16x16x32_bf16 v[108:111], v[138:141], v[166:169], v[108:111]
	v_mfma_f32_16x16x32_bf16 v[108:111], v[146:149], v[170:173], v[108:111]
	v_mfma_f32_16x16x32_bf16 v[92:95], v[138:141], v[174:177], v[92:95]
	v_mfma_f32_16x16x32_bf16 v[92:95], v[146:149], v[178:181], v[92:95]
	v_mfma_f32_16x16x32_bf16 v[76:79], v[138:141], v[204:207], v[76:79]
	v_mfma_f32_16x16x32_bf16 v[76:79], v[146:149], v[208:211], v[76:79]
	v_mfma_f32_16x16x32_bf16 v[72:75], v[150:153], v[204:207], v[72:75]
	v_mfma_f32_16x16x32_bf16 v[72:75], v[154:157], v[208:211], v[72:75]
	v_mfma_f32_16x16x32_bf16 v[88:91], v[150:153], v[174:177], v[88:91]
	v_mfma_f32_16x16x32_bf16 v[88:91], v[154:157], v[178:181], v[88:91]
	v_mfma_f32_16x16x32_bf16 v[104:107], v[150:153], v[166:169], v[104:107]
	v_mfma_f32_16x16x32_bf16 v[104:107], v[154:157], v[170:173], v[104:107]
	v_mfma_f32_16x16x32_bf16 v[120:123], v[150:153], v[158:161], v[120:123]
	v_mfma_f32_16x16x32_bf16 v[120:123], v[154:157], v[162:165], v[120:123]
	s_barrier
	s_add_i32 s56, 0, 0x14000
	s_add_i32 s52, s52, s38
	ds_read_b128 v[212:215], v143 offset:16384
	ds_read_b128 v[216:219], v143 offset:17408
	ds_read_b128 v[220:223], v143 offset:18432
	ds_read_b128 v[224:227], v143 offset:19456
	s_mov_b32 m0, s52
	s_add_u32 s98, s30, s58
	s_addc_u32 s99, s31, s59
	global_load_lds_dwordx4 v184, s[30:31]
	s_add_i32 m0, s52, 0x2000
	s_nop 0
	global_load_lds_dwordx4 v132, s[30:31]
	s_barrier
	s_waitcnt lgkmcnt(0)
	v_mfma_f32_16x16x32_bf16 v[116:119], v[212:215], v[158:161], v[116:119]
	v_mfma_f32_16x16x32_bf16 v[116:119], v[216:219], v[162:165], v[116:119]
	v_mfma_f32_16x16x32_bf16 v[100:103], v[212:215], v[166:169], v[100:103]
	v_mfma_f32_16x16x32_bf16 v[100:103], v[216:219], v[170:173], v[100:103]
	v_mfma_f32_16x16x32_bf16 v[84:87], v[212:215], v[174:177], v[84:87]
	v_mfma_f32_16x16x32_bf16 v[84:87], v[216:219], v[178:181], v[84:87]
	v_mfma_f32_16x16x32_bf16 v[68:71], v[212:215], v[204:207], v[68:71]
	v_mfma_f32_16x16x32_bf16 v[68:71], v[216:219], v[208:211], v[68:71]
	v_mfma_f32_16x16x32_bf16 v[64:67], v[220:223], v[204:207], v[64:67]
	v_mfma_f32_16x16x32_bf16 v[64:67], v[224:227], v[208:211], v[64:67]
	v_mfma_f32_16x16x32_bf16 v[80:83], v[220:223], v[174:177], v[80:83]
	v_mfma_f32_16x16x32_bf16 v[80:83], v[224:227], v[178:181], v[80:83]
	v_mfma_f32_16x16x32_bf16 v[96:99], v[220:223], v[166:169], v[96:99]
	v_mfma_f32_16x16x32_bf16 v[96:99], v[224:227], v[170:173], v[96:99]
	v_mfma_f32_16x16x32_bf16 v[112:115], v[220:223], v[158:161], v[112:115]
	v_mfma_f32_16x16x32_bf16 v[112:115], v[224:227], v[162:165], v[112:115]
	s_mov_b32 m0, s27
	s_barrier
	ds_read_b128 v[158:161], v145 offset:16384
	ds_read_b128 v[162:165], v145 offset:17408
	ds_read_b128 v[166:169], v145 offset:18432
	ds_read_b128 v[170:173], v145 offset:19456
	ds_read_b128 v[174:177], v145 offset:20480
	ds_read_b128 v[178:181], v145 offset:21504
	ds_read_b128 v[204:207], v145 offset:22528
	ds_read_b128 v[208:211], v145 offset:23552
	global_load_lds_dwordx4 v128, s[34:35]
	s_add_u32 s100, s34, s58
	s_addc_u32 s101, s35, s59
	s_mov_b32 m0, s29
	s_nop 0
	global_load_lds_dwordx4 v130, s[34:35]
	s_barrier
	s_waitcnt lgkmcnt(0)
	v_mfma_f32_16x16x32_bf16 v[60:63], v[138:141], v[158:161], v[60:63]
	v_mfma_f32_16x16x32_bf16 v[60:63], v[146:149], v[162:165], v[60:63]
	v_mfma_f32_16x16x32_bf16 v[44:47], v[138:141], v[166:169], v[44:47]
	v_mfma_f32_16x16x32_bf16 v[44:47], v[146:149], v[170:173], v[44:47]
	v_mfma_f32_16x16x32_bf16 v[28:31], v[138:141], v[174:177], v[28:31]
	v_mfma_f32_16x16x32_bf16 v[28:31], v[146:149], v[178:181], v[28:31]
	v_mfma_f32_16x16x32_bf16 v[12:15], v[138:141], v[204:207], v[12:15]
	v_mfma_f32_16x16x32_bf16 v[12:15], v[146:149], v[208:211], v[12:15]
	v_mfma_f32_16x16x32_bf16 v[8:11], v[150:153], v[204:207], v[8:11]
	v_mfma_f32_16x16x32_bf16 v[8:11], v[154:157], v[208:211], v[8:11]
	v_mfma_f32_16x16x32_bf16 v[24:27], v[150:153], v[174:177], v[24:27]
	v_mfma_f32_16x16x32_bf16 v[24:27], v[154:157], v[178:181], v[24:27]
	v_mfma_f32_16x16x32_bf16 v[40:43], v[150:153], v[166:169], v[40:43]
	v_mfma_f32_16x16x32_bf16 v[40:43], v[154:157], v[170:173], v[40:43]
	v_mfma_f32_16x16x32_bf16 v[56:59], v[150:153], v[158:161], v[56:59]
	v_mfma_f32_16x16x32_bf16 v[56:59], v[154:157], v[162:165], v[56:59]
	s_barrier
	s_add_u32 s54, s30, 0x80000
	s_addc_u32 s55, s31, 0
	s_add_i32 s52, s56, s38
	s_mov_b32 m0, s52
	s_nop 0
	global_load_lds_dwordx4 v184, s[54:55]
	s_add_i32 m0, s52, 0x2000
	s_nop 0
	global_load_lds_dwordx4 v132, s[54:55]
	s_waitcnt vmcnt(6)
	s_barrier
; #define PG8_STAGE(bufoff, gbase, voff) do { _Pragma("unroll") for (int _i = 0; _i < 2; ++_i) \
;         __builtin_amdgcn_global_load_lds((const unsigned*)((const char*)(gbase) + (voff)[_i]), (LAS unsigned*)(lds + (bufoff) + ldsw + _i * 8192), 16, 0, 0); } while (0)
; #define PG8_LDA(dst, b, h) do { _Pragma("unroll") for (int m = 0; m < 4; ++m) _Pragma("unroll") for (int k = 0; k < 2; ++k) dst[m][k] = *(const LAS bf16x8*)(lds + PG8_SA(b, h) + aoff + m * 2048 + k * 1024); } while (0)
; #define PG8_LDB(dst, b, h) do { _Pragma("unroll") for (int n = 0; n < 2; ++n) _Pragma("unroll") for (int k = 0; k < 2; ++k) dst[n][k] = *(const LAS bf16x8*)(lds + PG8_SB(b, h) + boff + n * 2048 + k * 1024); } while (0)
; #define PG8_MMA(ai, bj, At, Bt) do { __builtin_amdgcn_s_setprio(1); _Pragma("unroll") for (int m = 0; m < 4; ++m) _Pragma("unroll") for (int n = 0; n < 2; ++n) _Pragma("unroll") for (int k = 0; k < 2; ++k) \
;         acc[ai][bj][m][n] = __builtin_amdgcn_mfma_f32_16x16x32_bf16(Bt[n][k], At[m][k], acc[ai][bj][m][n], 0, 0, 0); __builtin_amdgcn_s_setprio(0); } while (0)
; #define PG8_WAIT_V(n) asm volatile("s_waitcnt vmcnt(" #n ")" ::: "memory")
; #define PG8_WAIT_L(n) asm volatile("s_waitcnt lgkmcnt(" #n ")" ::: "memory")
; #define PG8_BAR __builtin_amdgcn_s_barrier()
; #define PG8_SCHED __builtin_amdgcn_sched_barrier(0)
; template <class Epi>
; __device__ __forceinline__ void gemm_phase(LAS unsigned char* lds, const Gemm g, const StaticOrder& S, const Epi& E) {
;     ...
;             PG8_WAIT_V(6); PG8_BAR; PG8_MMA(1, 1, At, B1); PG8_BAR;
;             PG8_LDB(B0, 1, 0); PG8_SCHED; PG8_LDA(At, 1, 0); PG8_STAGE(PG8_SA(0, 1), a2 + hstep, voffA);
;             PG8_WAIT_L(8); PG8_BAR; PG8_WAIT_L(0); PG8_MMA(0, 0, At, B0); PG8_BAR; PG8_SCHED;
;             PG8_LDB(B1, 1, 1); PG8_STAGE(PG8_SB(1, 0), b3, voffB);
;             PG8_BAR; PG8_WAIT_L(0); PG8_MMA(0, 1, At, B1); PG8_BAR;
	v_mfma_f32_16x16x32_bf16 v[52:55], v[212:215], v[158:161], v[52:55]
	v_mfma_f32_16x16x32_bf16 v[52:55], v[216:219], v[162:165], v[52:55]
	v_mfma_f32_16x16x32_bf16 v[36:39], v[212:215], v[166:169], v[36:39]
	v_mfma_f32_16x16x32_bf16 v[36:39], v[216:219], v[170:173], v[36:39]
	v_mfma_f32_16x16x32_bf16 v[20:23], v[212:215], v[174:177], v[20:23]
	v_mfma_f32_16x16x32_bf16 v[20:23], v[216:219], v[178:181], v[20:23]
	v_mfma_f32_16x16x32_bf16 v[4:7], v[212:215], v[204:207], v[4:7]
	v_mfma_f32_16x16x32_bf16 v[4:7], v[216:219], v[208:211], v[4:7]
	v_mfma_f32_16x16x32_bf16 v[0:3], v[220:223], v[204:207], v[0:3]
	v_mfma_f32_16x16x32_bf16 v[0:3], v[224:227], v[208:211], v[0:3]
	v_mfma_f32_16x16x32_bf16 v[16:19], v[220:223], v[174:177], v[16:19]
	v_mfma_f32_16x16x32_bf16 v[16:19], v[224:227], v[178:181], v[16:19]
	v_mfma_f32_16x16x32_bf16 v[32:35], v[220:223], v[166:169], v[32:35]
	v_mfma_f32_16x16x32_bf16 v[32:35], v[224:227], v[170:173], v[32:35]
	v_mfma_f32_16x16x32_bf16 v[48:51], v[220:223], v[158:161], v[48:51]
	v_mfma_f32_16x16x32_bf16 v[48:51], v[224:227], v[162:165], v[48:51]
	s_add_i32 s52, 0, 0x18000
	s_barrier
	ds_read_b128 v[138:141], v143 offset:32768
	ds_read_b128 v[146:149], v143 offset:33792
	ds_read_b128 v[150:153], v143 offset:34816
	ds_read_b128 v[154:157], v143 offset:35840
	s_add_u32 s34, s34, 0x80000
	s_addc_u32 s35, s35, 0
	s_mov_b32 m0, s39
	ds_read_b128 v[158:161], v145 offset:32768
	ds_read_b128 v[162:165], v145 offset:33792
	ds_read_b128 v[166:169], v145 offset:34816
	ds_read_b128 v[170:173], v145 offset:35840
	ds_read_b128 v[174:177], v145 offset:36864
	ds_read_b128 v[178:181], v145 offset:37888
	ds_read_b128 v[204:207], v145 offset:38912
	ds_read_b128 v[208:211], v145 offset:39936
	global_load_lds_dwordx4 v128, s[34:35]
	s_mov_b32 m0, s40
	s_nop 0
	global_load_lds_dwordx4 v130, s[34:35]
	s_waitcnt lgkmcnt(8)
	s_barrier
	s_waitcnt lgkmcnt(0)
	v_mfma_f32_16x16x32_bf16 v[124:127], v[138:141], v[158:161], v[124:127]
	v_mfma_f32_16x16x32_bf16 v[124:127], v[146:149], v[162:165], v[124:127]
	v_mfma_f32_16x16x32_bf16 v[108:111], v[138:141], v[166:169], v[108:111]
	v_mfma_f32_16x16x32_bf16 v[108:111], v[146:149], v[170:173], v[108:111]
	v_mfma_f32_16x16x32_bf16 v[92:95], v[138:141], v[174:177], v[92:95]
	v_mfma_f32_16x16x32_bf16 v[92:95], v[146:149], v[178:181], v[92:95]
	v_mfma_f32_16x16x32_bf16 v[76:79], v[138:141], v[204:207], v[76:79]
	v_mfma_f32_16x16x32_bf16 v[76:79], v[146:149], v[208:211], v[76:79]
	v_mfma_f32_16x16x32_bf16 v[72:75], v[150:153], v[204:207], v[72:75]
	v_mfma_f32_16x16x32_bf16 v[72:75], v[154:157], v[208:211], v[72:75]
	v_mfma_f32_16x16x32_bf16 v[88:91], v[150:153], v[174:177], v[88:91]
	v_mfma_f32_16x16x32_bf16 v[88:91], v[154:157], v[178:181], v[88:91]
	v_mfma_f32_16x16x32_bf16 v[104:107], v[150:153], v[166:169], v[104:107]
	v_mfma_f32_16x16x32_bf16 v[104:107], v[154:157], v[170:173], v[104:107]
	v_mfma_f32_16x16x32_bf16 v[120:123], v[150:153], v[158:161], v[120:123]
	v_mfma_f32_16x16x32_bf16 v[120:123], v[154:157], v[162:165], v[120:123]
	s_barrier
	s_add_i32 s34, 0, 0x1c000
	s_add_i32 s35, s52, s38
	s_mov_b32 m0, s35
	ds_read_b128 v[212:215], v143 offset:49152
	ds_read_b128 v[216:219], v143 offset:50176
	ds_read_b128 v[220:223], v143 offset:51200
	ds_read_b128 v[224:227], v143 offset:52224
	global_load_lds_dwordx4 v184, s[98:99]
	s_add_i32 m0, s35, 0x2000
	s_nop 0
	global_load_lds_dwordx4 v132, s[98:99]
	s_barrier
	s_waitcnt lgkmcnt(0)
	v_mfma_f32_16x16x32_bf16 v[116:119], v[212:215], v[158:161], v[116:119]
	v_mfma_f32_16x16x32_bf16 v[116:119], v[216:219], v[162:165], v[116:119]
	v_mfma_f32_16x16x32_bf16 v[100:103], v[212:215], v[166:169], v[100:103]
	v_mfma_f32_16x16x32_bf16 v[100:103], v[216:219], v[170:173], v[100:103]
	v_mfma_f32_16x16x32_bf16 v[84:87], v[212:215], v[174:177], v[84:87]
	v_mfma_f32_16x16x32_bf16 v[84:87], v[216:219], v[178:181], v[84:87]
	v_mfma_f32_16x16x32_bf16 v[68:71], v[212:215], v[204:207], v[68:71]
	v_mfma_f32_16x16x32_bf16 v[68:71], v[216:219], v[208:211], v[68:71]
	v_mfma_f32_16x16x32_bf16 v[64:67], v[220:223], v[204:207], v[64:67]
	v_mfma_f32_16x16x32_bf16 v[64:67], v[224:227], v[208:211], v[64:67]
	v_mfma_f32_16x16x32_bf16 v[80:83], v[220:223], v[174:177], v[80:83]
	v_mfma_f32_16x16x32_bf16 v[80:83], v[224:227], v[178:181], v[80:83]
	v_mfma_f32_16x16x32_bf16 v[96:99], v[220:223], v[166:169], v[96:99]
	v_mfma_f32_16x16x32_bf16 v[96:99], v[224:227], v[170:173], v[96:99]
	v_mfma_f32_16x16x32_bf16 v[112:115], v[220:223], v[158:161], v[112:115]
	v_mfma_f32_16x16x32_bf16 v[112:115], v[224:227], v[162:165], v[112:115]
	s_mov_b32 m0, s41
	s_barrier
; __device__ __forceinline__ float sigmoidf_(float x) { return __builtin_amdgcn_rcpf(1.0f + __builtin_amdgcn_exp2f(-1.4426950408889634f * x)); }
; #define PG8_STAGE(bufoff, gbase, voff) do { _Pragma("unroll") for (int _i = 0; _i < 2; ++_i) \
;         __builtin_amdgcn_global_load_lds((const unsigned*)((const char*)(gbase) + (voff)[_i]), (LAS unsigned*)(lds + (bufoff) + ldsw + _i * 8192), 16, 0, 0); } while (0)
; #define PG8_LDA(dst, b, h) do { _Pragma("unroll") for (int m = 0; m < 4; ++m) _Pragma("unroll") for (int k = 0; k < 2; ++k) dst[m][k] = *(const LAS bf16x8*)(lds + PG8_SA(b, h) + aoff + m * 2048 + k * 1024); } while (0)
; #define PG8_MMA(ai, bj, At, Bt) do { __builtin_amdgcn_s_setprio(1); _Pragma("unroll") for (int m = 0; m < 4; ++m) _Pragma("unroll") for (int n = 0; n < 2; ++n) _Pragma("unroll") for (int k = 0; k < 2; ++k) \
;         acc[ai][bj][m][n] = __builtin_amdgcn_mfma_f32_16x16x32_bf16(Bt[n][k], At[m][k], acc[ai][bj][m][n], 0, 0, 0); __builtin_amdgcn_s_setprio(0); } while (0)
; #define PG8_WAIT_V(n) asm volatile("s_waitcnt vmcnt(" #n ")" ::: "memory")
; #define PG8_WAIT_L(n) asm volatile("s_waitcnt lgkmcnt(" #n ")" ::: "memory")
; #define PG8_BAR __builtin_amdgcn_s_barrier()
; #define PG8_SCHED __builtin_amdgcn_sched_barrier(0)
; template <class Epi>
; __device__ __forceinline__ void gemm_phase(LAS unsigned char* lds, const Gemm g, const StaticOrder& S, const Epi& E) {
;     ...
;             PG8_LDA(At, 1, 1); PG8_STAGE(PG8_SA(1, 0), a3, voffA);
;             PG8_BAR; PG8_WAIT_L(0); PG8_MMA(1, 0, At, B0); PG8_BAR; PG8_SCHED;
;             PG8_STAGE(PG8_SB(1, 1), b3 + hstep, voffB);
;             PG8_WAIT_V(6); PG8_BAR; PG8_MMA(1, 1, At, B1); PG8_BAR;
;     __device__ __forceinline__ void operator()(const Acc& acc, const Unit& u, int wr, int wc, int fr, int fq) const {
;     ...
;                 for (int bj = 0; bj < 2; ++bj) { f32x4 v0 = acc[ai][bj][m][0], v1 = acc[ai][bj][m][1];
;                     if (act) {
; #pragma unroll
;                         for (int j = 0; j < 4; ++j) { v0[j] = sigmoidf_(v0[j]); v1[j] = sigmoidf_(v1[j]); } }
	ds_read_b128 v[158:161], v145 offset:49152
	ds_read_b128 v[162:165], v145 offset:50176
	ds_read_b128 v[166:169], v145 offset:51200
	ds_read_b128 v[170:173], v145 offset:52224
	ds_read_b128 v[174:177], v145 offset:53248
	ds_read_b128 v[178:181], v145 offset:54272
	ds_read_b128 v[204:207], v145 offset:55296
	ds_read_b128 v[208:211], v145 offset:56320
	global_load_lds_dwordx4 v128, s[100:101]
	s_mov_b32 m0, s42
	s_nop 0
	global_load_lds_dwordx4 v130, s[100:101]
	s_barrier
	s_waitcnt lgkmcnt(0)
	v_mfma_f32_16x16x32_bf16 v[60:63], v[138:141], v[158:161], v[60:63]
	v_mfma_f32_16x16x32_bf16 v[60:63], v[146:149], v[162:165], v[60:63]
	v_mfma_f32_16x16x32_bf16 v[44:47], v[138:141], v[166:169], v[44:47]
	v_mfma_f32_16x16x32_bf16 v[44:47], v[146:149], v[170:173], v[44:47]
	v_mfma_f32_16x16x32_bf16 v[28:31], v[138:141], v[174:177], v[28:31]
	v_mfma_f32_16x16x32_bf16 v[28:31], v[146:149], v[178:181], v[28:31]
	v_mfma_f32_16x16x32_bf16 v[12:15], v[138:141], v[204:207], v[12:15]
	v_mfma_f32_16x16x32_bf16 v[12:15], v[146:149], v[208:211], v[12:15]
	v_mfma_f32_16x16x32_bf16 v[8:11], v[150:153], v[204:207], v[8:11]
	v_mfma_f32_16x16x32_bf16 v[8:11], v[154:157], v[208:211], v[8:11]
	v_mfma_f32_16x16x32_bf16 v[24:27], v[150:153], v[174:177], v[24:27]
	v_mfma_f32_16x16x32_bf16 v[24:27], v[154:157], v[178:181], v[24:27]
	v_mfma_f32_16x16x32_bf16 v[40:43], v[150:153], v[166:169], v[40:43]
	v_mfma_f32_16x16x32_bf16 v[40:43], v[154:157], v[170:173], v[40:43]
	v_mfma_f32_16x16x32_bf16 v[56:59], v[150:153], v[158:161], v[56:59]
	v_mfma_f32_16x16x32_bf16 v[56:59], v[154:157], v[162:165], v[56:59]
	s_barrier
	s_add_u32 s30, s30, 0x80080
	s_addc_u32 s31, s31, 0
	s_add_i32 s34, s34, s38
	s_mov_b32 m0, s34
	s_nop 0
	global_load_lds_dwordx4 v184, s[30:31]
	s_add_i32 m0, s34, 0x2000
	s_nop 0
	global_load_lds_dwordx4 v132, s[30:31]
	s_waitcnt vmcnt(6)
	s_barrier
	v_mfma_f32_16x16x32_bf16 v[52:55], v[212:215], v[158:161], v[52:55]
	v_mfma_f32_16x16x32_bf16 v[52:55], v[216:219], v[162:165], v[52:55]
	v_mfma_f32_16x16x32_bf16 v[36:39], v[212:215], v[166:169], v[36:39]
	v_mfma_f32_16x16x32_bf16 v[36:39], v[216:219], v[170:173], v[36:39]
	v_mfma_f32_16x16x32_bf16 v[20:23], v[212:215], v[174:177], v[20:23]
	v_mfma_f32_16x16x32_bf16 v[20:23], v[216:219], v[178:181], v[20:23]
	v_mfma_f32_16x16x32_bf16 v[4:7], v[212:215], v[204:207], v[4:7]
	v_mfma_f32_16x16x32_bf16 v[4:7], v[216:219], v[208:211], v[4:7]
	v_mfma_f32_16x16x32_bf16 v[0:3], v[220:223], v[204:207], v[0:3]
	v_mfma_f32_16x16x32_bf16 v[0:3], v[224:227], v[208:211], v[0:3]
	v_mfma_f32_16x16x32_bf16 v[16:19], v[220:223], v[174:177], v[16:19]
	v_mfma_f32_16x16x32_bf16 v[16:19], v[224:227], v[178:181], v[16:19]
	v_mfma_f32_16x16x32_bf16 v[32:35], v[220:223], v[166:169], v[32:35]
	v_mfma_f32_16x16x32_bf16 v[32:35], v[224:227], v[170:173], v[32:35]
	v_mfma_f32_16x16x32_bf16 v[48:51], v[220:223], v[158:161], v[48:51]
	v_mfma_f32_16x16x32_bf16 v[48:51], v[224:227], v[162:165], v[48:51]
	s_add_i32 s51, s51, 2
	s_add_u32 s8, s8, 0x100
	s_addc_u32 s9, s9, 0
	s_add_u32 s47, s47, 0x100
	s_addc_u32 s50, s50, 0
	s_cmp_gt_u32 s51, 29
	s_barrier
	s_cbranch_scc0 .LBB0_490
	v_cndmask_b32_e64 v138, 0, 1, s[16:17]
	v_cmp_ne_u32_e64 s[8:9], 1, v138
	s_andn2_b64 vcc, exec, s[16:17]
	s_cbranch_vccnz .LBB0_493
	v_mul_f32_e32 v124, 0xbfb8aa3b, v124
	v_mul_f32_e32 v120, 0xbfb8aa3b, v120
	v_mul_f32_e32 v125, 0xbfb8aa3b, v125
	v_mul_f32_e32 v121, 0xbfb8aa3b, v121
	v_mul_f32_e32 v126, 0xbfb8aa3b, v126
	v_mul_f32_e32 v122, 0xbfb8aa3b, v122
	v_mul_f32_e32 v127, 0xbfb8aa3b, v127
	v_mul_f32_e32 v123, 0xbfb8aa3b, v123
	v_exp_f32_e32 v124, v124
	v_exp_f32_e32 v120, v120
	v_exp_f32_e32 v125, v125
	v_exp_f32_e32 v121, v121
	v_exp_f32_e32 v126, v126
	v_exp_f32_e32 v122, v122
	v_exp_f32_e32 v127, v127
	v_exp_f32_e32 v123, v123
	v_add_f32_e32 v124, 1.0, v124
	v_add_f32_e32 v120, 1.0, v120
	v_add_f32_e32 v125, 1.0, v125
	v_add_f32_e32 v121, 1.0, v121
	v_add_f32_e32 v126, 1.0, v126
	v_add_f32_e32 v122, 1.0, v122
	v_add_f32_e32 v127, 1.0, v127
	v_add_f32_e32 v123, 1.0, v123
	v_rcp_f32_e32 v124, v124
	v_rcp_f32_e32 v120, v120
	v_rcp_f32_e32 v125, v125
	v_rcp_f32_e32 v121, v121
	v_rcp_f32_e32 v126, v126
	v_rcp_f32_e32 v122, v122
	v_rcp_f32_e32 v127, v127
	v_rcp_f32_e32 v123, v123

; #define PG8_STAGE(bufoff, gbase, voff) do { _Pragma("unroll") for (int _i = 0; _i < 2; ++_i) \
;         __builtin_amdgcn_global_load_lds((const unsigned*)((const char*)(gbase) + (voff)[_i]), (LAS unsigned*)(lds + (bufoff) + ldsw + _i * 8192), 16, 0, 0); } while (0)
; #define PG8_LDA(dst, b, h) do { _Pragma("unroll") for (int m = 0; m < 4; ++m) _Pragma("unroll") for (int k = 0; k < 2; ++k) dst[m][k] = *(const LAS bf16x8*)(lds + PG8_SA(b, h) + aoff + m * 2048 + k * 1024); } while (0)
; #define PG8_LDB(dst, b, h) do { _Pragma("unroll") for (int n = 0; n < 2; ++n) _Pragma("unroll") for (int k = 0; k < 2; ++k) dst[n][k] = *(const LAS bf16x8*)(lds + PG8_SB(b, h) + boff + n * 2048 + k * 1024); } while (0)
; #define PG8_MMA(ai, bj, At, Bt) do { __builtin_amdgcn_s_setprio(1); _Pragma("unroll") for (int m = 0; m < 4; ++m) _Pragma("unroll") for (int n = 0; n < 2; ++n) _Pragma("unroll") for (int k = 0; k < 2; ++k) \
;         acc[ai][bj][m][n] = __builtin_amdgcn_mfma_f32_16x16x32_bf16(Bt[n][k], At[m][k], acc[ai][bj][m][n], 0, 0, 0); __builtin_amdgcn_s_setprio(0); } while (0)
; #define PG8_WAIT_V(n) asm volatile("s_waitcnt vmcnt(" #n ")" ::: "memory")
; #define PG8_WAIT_L(n) asm volatile("s_waitcnt lgkmcnt(" #n ")" ::: "memory")
; #define PG8_BAR __builtin_amdgcn_s_barrier()
; template <class Epi>
; __device__ __forceinline__ void gemm_phase(LAS unsigned char* lds, const Gemm g, const StaticOrder& S, const Epi& E) {
;     ...
;             const bool last = (t == nt - 2);
;             const char* a1 = cA + (size_t)(t + 1) * kstep;
;             const char* a2 = last ? nA : cA + (size_t)(t + 2) * kstep; const char* b2 = last ? nB : cB + (size_t)(t + 2) * kstep;
;             const char* a3 = a2 + kstep; const char* b3 = b2 + kstep;
;             PG8_LDB(B0, 0, 0); PG8_SCHED; PG8_LDA(At, 0, 0); PG8_STAGE(PG8_SA(1, 1), a1 + hstep, voffA);
;             PG8_WAIT_L(8); PG8_BAR; PG8_WAIT_L(0); PG8_MMA(0, 0, At, B0); PG8_BAR; PG8_SCHED;
;             PG8_LDB(B1, 0, 1); PG8_STAGE(PG8_SB(0, 0), b2, voffB);
;             PG8_BAR; PG8_WAIT_L(0); PG8_MMA(0, 1, At, B1); PG8_BAR;
;             PG8_LDA(At, 0, 1); PG8_STAGE(PG8_SA(0, 0), a2, voffA);
;             PG8_BAR; PG8_WAIT_L(0); PG8_MMA(1, 0, At, B0); PG8_BAR; PG8_SCHED;
;             PG8_STAGE(PG8_SB(0, 1), b2 + hstep, voffB);
;             PG8_WAIT_V(6); PG8_BAR; PG8_MMA(1, 1, At, B1); PG8_BAR;
.LBB0_591:
	s_add_i32 s68, s8, 2
	s_add_u32 s36, s0, 0x80
	s_addc_u32 s9, s1, 0
	s_add_i32 s66, 0, 0x10000
	ds_read_b128 v[48:51], v233
	ds_read_b128 v[52:55], v233 offset:1024
	ds_read_b128 v[56:59], v233 offset:2048
	ds_read_b128 v[60:63], v233 offset:3072
	s_cmp_eq_u32 s55, s8
	s_cselect_b32 s8, s34, s36
	s_cselect_b32 s9, s35, s9
	s_cselect_b32 s37, s11, s63
	s_cselect_b32 s36, s10, s43
	s_add_i32 m0, s44, 0xc000
	ds_read_b128 v[68:71], v248
	ds_read_b128 v[76:79], v248 offset:1024
	ds_read_b128 v[80:83], v248 offset:2048
	ds_read_b128 v[84:87], v248 offset:3072
	ds_read_b128 v[160:163], v248 offset:4096
	ds_read_b128 v[164:167], v248 offset:5120
	ds_read_b128 v[168:171], v248 offset:6144
	ds_read_b128 v[172:175], v248 offset:7168
	global_load_lds_dwordx4 v214, s[0:1]
	s_add_i32 m0, s44, 0xe000
	s_nop 0
	global_load_lds_dwordx4 v216, s[0:1]
	s_waitcnt lgkmcnt(8)
	s_barrier
	s_waitcnt lgkmcnt(0)
	v_mfma_f32_16x16x32_bf16 v[156:159], v[48:51], v[68:71], v[156:159]
	v_mfma_f32_16x16x32_bf16 v[156:159], v[52:55], v[76:79], v[156:159]
	v_mfma_f32_16x16x32_bf16 v[140:143], v[48:51], v[80:83], v[140:143]
	v_mfma_f32_16x16x32_bf16 v[140:143], v[52:55], v[84:87], v[140:143]
	v_mfma_f32_16x16x32_bf16 v[124:127], v[48:51], v[160:163], v[124:127]
	v_mfma_f32_16x16x32_bf16 v[124:127], v[52:55], v[164:167], v[124:127]
	v_mfma_f32_16x16x32_bf16 v[108:111], v[48:51], v[168:171], v[108:111]
	v_mfma_f32_16x16x32_bf16 v[108:111], v[52:55], v[172:175], v[108:111]
	v_mfma_f32_16x16x32_bf16 v[104:107], v[56:59], v[168:171], v[104:107]
	v_mfma_f32_16x16x32_bf16 v[104:107], v[60:63], v[172:175], v[104:107]
	v_mfma_f32_16x16x32_bf16 v[120:123], v[56:59], v[160:163], v[120:123]
	v_mfma_f32_16x16x32_bf16 v[120:123], v[60:63], v[164:167], v[120:123]
	v_mfma_f32_16x16x32_bf16 v[136:139], v[56:59], v[80:83], v[136:139]
	v_mfma_f32_16x16x32_bf16 v[136:139], v[60:63], v[84:87], v[136:139]
	v_mfma_f32_16x16x32_bf16 v[152:155], v[56:59], v[68:71], v[152:155]
	v_mfma_f32_16x16x32_bf16 v[152:155], v[60:63], v[76:79], v[152:155]
	s_barrier
	s_add_i32 s67, 0, 0x14000
	s_add_i32 s66, s66, s41
	s_mov_b32 m0, s66
	ds_read_b128 v[176:179], v233 offset:16384
	ds_read_b128 v[180:183], v233 offset:17408
	ds_read_b128 v[218:221], v233 offset:18432
	ds_read_b128 v[222:225], v233 offset:19456
	global_load_lds_dwordx4 v184, s[36:37]
	s_add_u32 s98, s36, s58
	s_addc_u32 s99, s37, s59
	s_add_i32 m0, s66, 0x2000
	s_nop 0
	global_load_lds_dwordx4 v212, s[36:37]
	s_barrier
	s_waitcnt lgkmcnt(0)
	v_mfma_f32_16x16x32_bf16 v[148:151], v[176:179], v[68:71], v[148:151]
	v_mfma_f32_16x16x32_bf16 v[68:71], v[218:221], v[68:71], v[144:147]
	v_mfma_f32_16x16x32_bf16 v[148:151], v[180:183], v[76:79], v[148:151]
	v_mfma_f32_16x16x32_bf16 v[68:71], v[222:225], v[76:79], v[68:71]
	v_mfma_f32_16x16x32_bf16 v[76:79], v[176:179], v[80:83], v[132:135]
	v_mfma_f32_16x16x32_bf16 v[80:83], v[218:221], v[80:83], v[128:131]
	v_mfma_f32_16x16x32_bf16 v[112:115], v[218:221], v[160:163], v[112:115]
	v_mfma_f32_16x16x32_bf16 v[100:103], v[176:179], v[168:171], v[100:103]
	v_mfma_f32_16x16x32_bf16 v[96:99], v[218:221], v[168:171], v[96:99]
	v_mfma_f32_16x16x32_bf16 v[76:79], v[180:183], v[84:87], v[76:79]
	v_mfma_f32_16x16x32_bf16 v[80:83], v[222:225], v[84:87], v[80:83]
	v_mfma_f32_16x16x32_bf16 v[84:87], v[176:179], v[160:163], v[116:119]
	v_mfma_f32_16x16x32_bf16 v[112:115], v[222:225], v[164:167], v[112:115]
	v_mfma_f32_16x16x32_bf16 v[100:103], v[180:183], v[172:175], v[100:103]
	v_mfma_f32_16x16x32_bf16 v[96:99], v[222:225], v[172:175], v[96:99]
	v_mfma_f32_16x16x32_bf16 v[84:87], v[180:183], v[164:167], v[84:87]
	s_mov_b32 m0, s44
	s_barrier
	ds_read_b128 v[116:119], v248 offset:16384
	ds_read_b128 v[128:131], v248 offset:17408
	ds_read_b128 v[132:135], v248 offset:18432
	ds_read_b128 v[144:147], v248 offset:19456
	ds_read_b128 v[160:163], v248 offset:20480
	ds_read_b128 v[164:167], v248 offset:21504
	ds_read_b128 v[168:171], v248 offset:22528
	ds_read_b128 v[172:175], v248 offset:23552
	global_load_lds_dwordx4 v208, s[8:9]
	s_add_u32 s100, s8, s58
	s_addc_u32 s101, s9, s59
	s_mov_b32 m0, s45
	s_nop 0
	global_load_lds_dwordx4 v210, s[8:9]
	s_barrier
	s_waitcnt lgkmcnt(0)
	v_mfma_f32_16x16x32_bf16 v[92:95], v[48:51], v[116:119], v[92:95]
	v_mfma_f32_16x16x32_bf16 v[92:95], v[52:55], v[128:131], v[92:95]
	v_mfma_f32_16x16x32_bf16 v[44:47], v[48:51], v[132:135], v[44:47]
	v_mfma_f32_16x16x32_bf16 v[44:47], v[52:55], v[144:147], v[44:47]
	v_mfma_f32_16x16x32_bf16 v[28:31], v[48:51], v[160:163], v[28:31]
	v_mfma_f32_16x16x32_bf16 v[28:31], v[52:55], v[164:167], v[28:31]
	v_mfma_f32_16x16x32_bf16 v[12:15], v[48:51], v[168:171], v[12:15]
	v_mfma_f32_16x16x32_bf16 v[12:15], v[52:55], v[172:175], v[12:15]
	v_mfma_f32_16x16x32_bf16 v[8:11], v[56:59], v[168:171], v[8:11]
	v_mfma_f32_16x16x32_bf16 v[8:11], v[60:63], v[172:175], v[8:11]
	v_mfma_f32_16x16x32_bf16 v[24:27], v[56:59], v[160:163], v[24:27]
	v_mfma_f32_16x16x32_bf16 v[24:27], v[60:63], v[164:167], v[24:27]
	v_mfma_f32_16x16x32_bf16 v[40:43], v[56:59], v[132:135], v[40:43]
	v_mfma_f32_16x16x32_bf16 v[40:43], v[60:63], v[144:147], v[40:43]
	v_mfma_f32_16x16x32_bf16 v[88:91], v[56:59], v[116:119], v[88:91]
	v_mfma_f32_16x16x32_bf16 v[88:91], v[60:63], v[128:131], v[88:91]
	s_barrier
	s_add_u32 s36, s36, s52
	s_addc_u32 s37, s37, 0
	s_add_i32 s66, s67, s41
	v_lshl_add_u64 v[190:191], s[36:37], 0, v[184:185]
	s_mov_b32 m0, s66
	v_lshl_add_u64 v[192:193], s[36:37], 0, v[212:213]
	global_load_lds_dwordx4 v[190:191], off
	s_add_i32 m0, s66, 0x2000
	s_nop 0
	global_load_lds_dwordx4 v[192:193], off
	s_waitcnt vmcnt(6)
	s_barrier
; #define PG8_STAGE(bufoff, gbase, voff) do { _Pragma("unroll") for (int _i = 0; _i < 2; ++_i) \
;         __builtin_amdgcn_global_load_lds((const unsigned*)((const char*)(gbase) + (voff)[_i]), (LAS unsigned*)(lds + (bufoff) + ldsw + _i * 8192), 16, 0, 0); } while (0)
; #define PG8_LDA(dst, b, h) do { _Pragma("unroll") for (int m = 0; m < 4; ++m) _Pragma("unroll") for (int k = 0; k < 2; ++k) dst[m][k] = *(const LAS bf16x8*)(lds + PG8_SA(b, h) + aoff + m * 2048 + k * 1024); } while (0)
; #define PG8_LDB(dst, b, h) do { _Pragma("unroll") for (int n = 0; n < 2; ++n) _Pragma("unroll") for (int k = 0; k < 2; ++k) dst[n][k] = *(const LAS bf16x8*)(lds + PG8_SB(b, h) + boff + n * 2048 + k * 1024); } while (0)
; #define PG8_MMA(ai, bj, At, Bt) do { __builtin_amdgcn_s_setprio(1); _Pragma("unroll") for (int m = 0; m < 4; ++m) _Pragma("unroll") for (int n = 0; n < 2; ++n) _Pragma("unroll") for (int k = 0; k < 2; ++k) \
;         acc[ai][bj][m][n] = __builtin_amdgcn_mfma_f32_16x16x32_bf16(Bt[n][k], At[m][k], acc[ai][bj][m][n], 0, 0, 0); __builtin_amdgcn_s_setprio(0); } while (0)
; #define PG8_WAIT_V(n) asm volatile("s_waitcnt vmcnt(" #n ")" ::: "memory")
; #define PG8_WAIT_L(n) asm volatile("s_waitcnt lgkmcnt(" #n ")" ::: "memory")
; #define PG8_BAR __builtin_amdgcn_s_barrier()
; #define PG8_SCHED __builtin_amdgcn_sched_barrier(0)
; template <class Epi>
; __device__ __forceinline__ void gemm_phase(LAS unsigned char* lds, const Gemm g, const StaticOrder& S, const Epi& E) {
;     ...
;             PG8_WAIT_V(6); PG8_BAR; PG8_MMA(1, 1, At, B1); PG8_BAR;
;             PG8_LDB(B0, 1, 0); PG8_SCHED; PG8_LDA(At, 1, 0); PG8_STAGE(PG8_SA(0, 1), a2 + hstep, voffA);
;             PG8_WAIT_L(8); PG8_BAR; PG8_WAIT_L(0); PG8_MMA(0, 0, At, B0); PG8_BAR; PG8_SCHED;
;             PG8_LDB(B1, 1, 1); PG8_STAGE(PG8_SB(1, 0), b3, voffB);
;             PG8_BAR; PG8_WAIT_L(0); PG8_MMA(0, 1, At, B1); PG8_BAR;
	v_mfma_f32_16x16x32_bf16 v[36:39], v[176:179], v[132:135], v[36:39]
	v_mfma_f32_16x16x32_bf16 v[36:39], v[180:183], v[144:147], v[36:39]
	v_mfma_f32_16x16x32_bf16 v[20:23], v[176:179], v[160:163], v[20:23]
	v_mfma_f32_16x16x32_bf16 v[20:23], v[180:183], v[164:167], v[20:23]
	v_mfma_f32_16x16x32_bf16 v[4:7], v[176:179], v[168:171], v[4:7]
	v_mfma_f32_16x16x32_bf16 v[4:7], v[180:183], v[172:175], v[4:7]
	v_mfma_f32_16x16x32_bf16 v[48:51], v[176:179], v[116:119], v[72:75]
	v_mfma_f32_16x16x32_bf16 v[48:51], v[180:183], v[128:131], v[48:51]
	v_mfma_f32_16x16x32_bf16 v[52:55], v[218:221], v[116:119], v[64:67]
	v_mfma_f32_16x16x32_bf16 v[52:55], v[222:225], v[128:131], v[52:55]
	v_mfma_f32_16x16x32_bf16 v[0:3], v[218:221], v[168:171], v[0:3]
	v_mfma_f32_16x16x32_bf16 v[0:3], v[222:225], v[172:175], v[0:3]
	v_mfma_f32_16x16x32_bf16 v[16:19], v[218:221], v[160:163], v[16:19]
	v_mfma_f32_16x16x32_bf16 v[16:19], v[222:225], v[164:167], v[16:19]
	v_mfma_f32_16x16x32_bf16 v[32:35], v[218:221], v[132:135], v[32:35]
	v_mfma_f32_16x16x32_bf16 v[32:35], v[222:225], v[144:147], v[32:35]
	s_add_i32 s36, 0, 0x18000
	s_barrier
	ds_read_b128 v[56:59], v233 offset:32768
	ds_read_b128 v[60:63], v233 offset:33792
	ds_read_b128 v[64:67], v233 offset:34816
	ds_read_b128 v[72:75], v233 offset:35840
	s_add_u32 s8, s8, s52
	s_addc_u32 s9, s9, 0
	s_mov_b32 m0, s46
	ds_read_b128 v[116:119], v248 offset:32768
	ds_read_b128 v[128:131], v248 offset:33792
	ds_read_b128 v[160:163], v248 offset:34816
	ds_read_b128 v[164:167], v248 offset:35840
	ds_read_b128 v[168:171], v248 offset:36864
	ds_read_b128 v[172:175], v248 offset:37888
	ds_read_b128 v[176:179], v248 offset:38912
	ds_read_b128 v[180:183], v248 offset:39936
	global_load_lds_dwordx4 v208, s[8:9]
	v_lshl_add_u64 v[132:133], s[8:9], 0, v[210:211]
	s_mov_b32 m0, s47
	s_nop 0
	global_load_lds_dwordx4 v[132:133], off
	s_waitcnt lgkmcnt(8)
	s_barrier
	s_waitcnt lgkmcnt(0)
	v_mfma_f32_16x16x32_bf16 v[132:135], v[56:59], v[116:119], v[156:159]
	v_mfma_f32_16x16x32_bf16 v[156:159], v[60:63], v[128:131], v[132:135]
	v_mfma_f32_16x16x32_bf16 v[132:135], v[64:67], v[116:119], v[152:155]
	v_mfma_f32_16x16x32_bf16 v[152:155], v[72:75], v[128:131], v[132:135]
	v_mfma_f32_16x16x32_bf16 v[132:135], v[56:59], v[160:163], v[140:143]
	v_mfma_f32_16x16x32_bf16 v[140:143], v[60:63], v[164:167], v[132:135]
	v_mfma_f32_16x16x32_bf16 v[132:135], v[64:67], v[160:163], v[136:139]
	v_mfma_f32_16x16x32_bf16 v[124:127], v[56:59], v[168:171], v[124:127]
	v_mfma_f32_16x16x32_bf16 v[120:123], v[64:67], v[168:171], v[120:123]
	v_mfma_f32_16x16x32_bf16 v[108:111], v[56:59], v[176:179], v[108:111]
	v_mfma_f32_16x16x32_bf16 v[104:107], v[64:67], v[176:179], v[104:107]
	v_mfma_f32_16x16x32_bf16 v[136:139], v[72:75], v[164:167], v[132:135]
	v_mfma_f32_16x16x32_bf16 v[124:127], v[60:63], v[172:175], v[124:127]
	v_mfma_f32_16x16x32_bf16 v[120:123], v[72:75], v[172:175], v[120:123]
	v_mfma_f32_16x16x32_bf16 v[108:111], v[60:63], v[180:183], v[108:111]
	v_mfma_f32_16x16x32_bf16 v[104:107], v[72:75], v[180:183], v[104:107]
	s_barrier
	s_add_i32 s8, 0, 0x1c000
	s_add_i32 s9, s36, s41
	ds_read_b128 v[218:221], v233 offset:49152
	ds_read_b128 v[222:225], v233 offset:50176
	ds_read_b128 v[226:229], v233 offset:51200
	ds_read_b128 v[204:207], v233 offset:52224
	s_mov_b32 m0, s9
	s_nop 0
	global_load_lds_dwordx4 v184, s[98:99]
	s_add_i32 m0, s9, 0x2000
	s_nop 0
	global_load_lds_dwordx4 v212, s[98:99]
	s_barrier
	s_waitcnt lgkmcnt(0)
	v_mfma_f32_16x16x32_bf16 v[68:71], v[226:229], v[116:119], v[68:71]
	v_mfma_f32_16x16x32_bf16 v[132:135], v[218:221], v[116:119], v[148:151]
	v_mfma_f32_16x16x32_bf16 v[144:147], v[204:207], v[128:131], v[68:71]
	v_mfma_f32_16x16x32_bf16 v[68:71], v[218:221], v[160:163], v[76:79]
	v_mfma_f32_16x16x32_bf16 v[148:151], v[222:225], v[128:131], v[132:135]
	v_mfma_f32_16x16x32_bf16 v[132:135], v[222:225], v[164:167], v[68:71]
	v_mfma_f32_16x16x32_bf16 v[68:71], v[226:229], v[160:163], v[80:83]
	v_mfma_f32_16x16x32_bf16 v[128:131], v[204:207], v[164:167], v[68:71]
	v_mfma_f32_16x16x32_bf16 v[68:71], v[218:221], v[168:171], v[84:87]
	v_mfma_f32_16x16x32_bf16 v[116:119], v[222:225], v[172:175], v[68:71]
	v_mfma_f32_16x16x32_bf16 v[68:71], v[226:229], v[168:171], v[112:115]
	v_mfma_f32_16x16x32_bf16 v[112:115], v[204:207], v[172:175], v[68:71]
	v_mfma_f32_16x16x32_bf16 v[68:71], v[218:221], v[176:179], v[100:103]
	v_mfma_f32_16x16x32_bf16 v[100:103], v[222:225], v[180:183], v[68:71]
	v_mfma_f32_16x16x32_bf16 v[68:71], v[226:229], v[176:179], v[96:99]
	v_mfma_f32_16x16x32_bf16 v[96:99], v[204:207], v[180:183], v[68:71]
	s_mov_b32 m0, s50
	s_barrier
; #define PG8_STAGE(bufoff, gbase, voff) do { _Pragma("unroll") for (int _i = 0; _i < 2; ++_i) \
;         __builtin_amdgcn_global_load_lds((const unsigned*)((const char*)(gbase) + (voff)[_i]), (LAS unsigned*)(lds + (bufoff) + ldsw + _i * 8192), 16, 0, 0); } while (0)
; #define PG8_LDA(dst, b, h) do { _Pragma("unroll") for (int m = 0; m < 4; ++m) _Pragma("unroll") for (int k = 0; k < 2; ++k) dst[m][k] = *(const LAS bf16x8*)(lds + PG8_SA(b, h) + aoff + m * 2048 + k * 1024); } while (0)
; #define PG8_MMA(ai, bj, At, Bt) do { __builtin_amdgcn_s_setprio(1); _Pragma("unroll") for (int m = 0; m < 4; ++m) _Pragma("unroll") for (int n = 0; n < 2; ++n) _Pragma("unroll") for (int k = 0; k < 2; ++k) \
;         acc[ai][bj][m][n] = __builtin_amdgcn_mfma_f32_16x16x32_bf16(Bt[n][k], At[m][k], acc[ai][bj][m][n], 0, 0, 0); __builtin_amdgcn_s_setprio(0); } while (0)
; #define PG8_WAIT_V(n) asm volatile("s_waitcnt vmcnt(" #n ")" ::: "memory")
; #define PG8_WAIT_L(n) asm volatile("s_waitcnt lgkmcnt(" #n ")" ::: "memory")
; #define PG8_BAR __builtin_amdgcn_s_barrier()
; #define PG8_SCHED __builtin_amdgcn_sched_barrier(0)
; template <class Epi>
; __device__ __forceinline__ void gemm_phase(LAS unsigned char* lds, const Gemm g, const StaticOrder& S, const Epi& E) {
;     ...
;             PG8_LDA(At, 1, 1); PG8_STAGE(PG8_SA(1, 0), a3, voffA);
;             PG8_BAR; PG8_WAIT_L(0); PG8_MMA(1, 0, At, B0); PG8_BAR; PG8_SCHED;
;             PG8_STAGE(PG8_SB(1, 1), b3 + hstep, voffB);
;             PG8_WAIT_V(6); PG8_BAR; PG8_MMA(1, 1, At, B1); PG8_BAR;
;     __device__ __forceinline__ void operator()(const Acc& acc, const Unit& u, int wr, int wc, int fr, int fq) const {
;     ...
;         if (stats) {
; #pragma unroll
;             for (int bj = 0; bj < 2; ++bj)
; #pragma unroll
;                 for (int n = 0; n < 2; ++n) { gv[bj][n] = *(const f32x4*)(lg + col0 + bj * 128 + n * 4); bv[bj][n] = *(const f32x4*)(lb + col0 + bj * 128 + n * 4); } }
	s_nop 2
	ds_read_b128 v[68:71], v248 offset:49152
	ds_read_b128 v[76:79], v248 offset:50176
	ds_read_b128 v[80:83], v248 offset:51200
	ds_read_b128 v[84:87], v248 offset:52224
	ds_read_b128 v[160:163], v248 offset:53248
	ds_read_b128 v[164:167], v248 offset:54272
	ds_read_b128 v[168:171], v248 offset:55296
	ds_read_b128 v[172:175], v248 offset:56320
	global_load_lds_dwordx4 v208, s[100:101]
	s_mov_b32 m0, s51
	s_nop 0
	global_load_lds_dwordx4 v210, s[100:101]
	s_barrier
	s_waitcnt lgkmcnt(0)
	v_mfma_f32_16x16x32_bf16 v[92:95], v[56:59], v[68:71], v[92:95]
	v_mfma_f32_16x16x32_bf16 v[92:95], v[60:63], v[76:79], v[92:95]
	v_mfma_f32_16x16x32_bf16 v[44:47], v[56:59], v[80:83], v[44:47]
	v_mfma_f32_16x16x32_bf16 v[44:47], v[60:63], v[84:87], v[44:47]
	v_mfma_f32_16x16x32_bf16 v[28:31], v[56:59], v[160:163], v[28:31]
	v_mfma_f32_16x16x32_bf16 v[28:31], v[60:63], v[164:167], v[28:31]
	v_mfma_f32_16x16x32_bf16 v[12:15], v[56:59], v[168:171], v[12:15]
	v_mfma_f32_16x16x32_bf16 v[12:15], v[60:63], v[172:175], v[12:15]
	v_mfma_f32_16x16x32_bf16 v[8:11], v[64:67], v[168:171], v[8:11]
	v_mfma_f32_16x16x32_bf16 v[8:11], v[72:75], v[172:175], v[8:11]
	v_mfma_f32_16x16x32_bf16 v[24:27], v[64:67], v[160:163], v[24:27]
	v_mfma_f32_16x16x32_bf16 v[24:27], v[72:75], v[164:167], v[24:27]
	v_mfma_f32_16x16x32_bf16 v[40:43], v[64:67], v[80:83], v[40:43]
	v_mfma_f32_16x16x32_bf16 v[40:43], v[72:75], v[84:87], v[40:43]
	v_mfma_f32_16x16x32_bf16 v[88:91], v[64:67], v[68:71], v[88:91]
	v_mfma_f32_16x16x32_bf16 v[88:91], v[72:75], v[76:79], v[88:91]
	s_barrier
	s_add_i32 s8, s8, s41
	v_lshl_add_u64 v[56:57], v[190:191], 0, s[58:59]
	s_mov_b32 m0, s8
	s_nop 0
	global_load_lds_dwordx4 v[56:57], off
	v_lshl_add_u64 v[56:57], v[192:193], 0, s[58:59]
	s_add_i32 m0, s8, 0x2000
	s_nop 0
	global_load_lds_dwordx4 v[56:57], off
	s_waitcnt vmcnt(6)
	s_barrier
	v_mfma_f32_16x16x32_bf16 v[48:51], v[218:221], v[68:71], v[48:51]
	v_mfma_f32_16x16x32_bf16 v[72:75], v[222:225], v[76:79], v[48:51]
	v_mfma_f32_16x16x32_bf16 v[48:51], v[226:229], v[68:71], v[52:55]
	v_mfma_f32_16x16x32_bf16 v[36:39], v[218:221], v[80:83], v[36:39]
	v_mfma_f32_16x16x32_bf16 v[32:35], v[226:229], v[80:83], v[32:35]
	v_mfma_f32_16x16x32_bf16 v[20:23], v[218:221], v[160:163], v[20:23]
	v_mfma_f32_16x16x32_bf16 v[16:19], v[226:229], v[160:163], v[16:19]
	v_mfma_f32_16x16x32_bf16 v[4:7], v[218:221], v[168:171], v[4:7]
	v_mfma_f32_16x16x32_bf16 v[0:3], v[226:229], v[168:171], v[0:3]
	v_mfma_f32_16x16x32_bf16 v[64:67], v[204:207], v[76:79], v[48:51]
	v_mfma_f32_16x16x32_bf16 v[36:39], v[222:225], v[84:87], v[36:39]
	v_mfma_f32_16x16x32_bf16 v[32:35], v[204:207], v[84:87], v[32:35]
	v_mfma_f32_16x16x32_bf16 v[20:23], v[222:225], v[164:167], v[20:23]
	v_mfma_f32_16x16x32_bf16 v[16:19], v[204:207], v[164:167], v[16:19]
	v_mfma_f32_16x16x32_bf16 v[4:7], v[222:225], v[172:175], v[4:7]
	v_mfma_f32_16x16x32_bf16 v[0:3], v[204:207], v[172:175], v[0:3]
	s_add_u32 s0, s0, 0x100
	s_addc_u32 s1, s1, 0
	s_add_u32 s43, s43, 0x100
	s_addc_u32 s63, s63, 0
	s_cmp_ge_u32 s68, s54
	s_mov_b32 s8, s68
	s_barrier
	s_cbranch_scc0 .LBB0_591
	v_lshl_or_b32 v224, s42, 8, v247
	v_cndmask_b32_e64 v48, 0, 1, s[30:31]
	v_cmp_ne_u32_e64 s[8:9], 1, v48
	s_andn2_b64 vcc, exec, s[30:31]
	v_ashrrev_i32_e32 v225, 31, v224
	s_cbranch_vccnz .LBB0_594
	v_lshlrev_b64 v[48:49], 2, v[224:225]
	v_lshl_add_u64 v[52:53], s[20:21], 0, v[48:49]
	v_lshl_add_u64 v[60:61], s[22:23], 0, v[48:49]
	global_load_dwordx4 v[68:71], v[52:53], off offset:16
	global_load_dwordx4 v[80:83], v[52:53], off
	global_load_dwordx4 v[76:79], v[60:61], off offset:16
	global_load_dwordx4 v[84:87], v[60:61], off
	global_load_dwordx4 v[48:51], v[52:53], off offset:528
	global_load_dwordx4 v[56:59], v[52:53], off offset:512
	s_nop 0
	global_load_dwordx4 v[52:55], v[60:61], off offset:528
	s_nop 0
	global_load_dwordx4 v[60:63], v[60:61], off offset:512
